# rg local tile (P3): each block touches the conv input rows of its next rg tile during the tile's last stage
# baseline (speedup 1.0000x reference)
; __device__ __forceinline__ float bf2f(bf16_t h) { return __uint_as_float(((unsigned)h) << 16); }
; __device__ void rg_tile(unsigned char* lds, const Params& p, int l, int b, int ck, int hh, bool outmode) {
;     ...
;   const bool isctx = ck < 4;
;   const int L = isctx ? 256 : 2048;
;   const int t0 = isctx ? ck * 64 : (ck - 4) * 64;
;   const int rowbase = isctx ? (NLAT + b * 256) : (b * 2048);
;   float car_pre = 0.f, gp_pre[8];
;   {
;     const int d_ = (tid >> 6) & 1, j_ = tid & 63;
;     if (outmode) {
;       car_pre = car[((size_t)(b * 36 + ck) * 2 + d_) * 256 + hh * 64 + j_];
; #pragma unroll
;       for (int q = 0; q < 8; ++q) gp_pre[q] = bf2f(z[(size_t)(rowbase + t0 + w * 8 + q) * ZS + 2816 + 256 + hh * 64 + lane]);
;     } else {
; #pragma unroll
;       for (int q = 0; q < 8; ++q) gp_pre[q] = 0.f;
;     }
;   }
;   const int chm_ = hh * 64 + (w & 3) * 16 + lr, dm_ = w >> 2;
;   const float br = p.in[22][(size_t)l * 1024 + (dm_ * 2 + 0) * 256 + chm_];
;   const float bi = p.in[22][(size_t)l * 1024 + (dm_ * 2 + 1) * 256 + chm_];
;   const float lam_ = p.in[23][(size_t)l * 512 + dm_ * 256 + chm_];
;   {
;     const int i = tid & 63, tq = tid >> 6;
;     const int ch = hh * 64 + i;
;     const float* wc = p.in[20] + (size_t)l * 4 * 256 + ch;
;     const float w0 = wc[0], w1 = wc[256], w2 = wc[512], w3 = wc[768];
; #pragma unroll
;     for (int ii = 0; ii < 8; ++ii) {
;       const int tt = tq * 8 + ii;
;       const int tp = t0 + tt;
;       const int tm1 = tp - 1 >= 0 ? tp - 1 : 0, tp1 = tp + 1 < L ? tp + 1 : L - 1, tp2 = tp + 2 < L ? tp + 2 : L - 1;
;       const float z0 = bf2f(z[(size_t)(rowbase + tm1) * ZS + 2816 + ch]);
;       const float z1 = bf2f(z[(size_t)(rowbase + tp) * ZS + 2816 + ch]);
;       const float z2 = bf2f(z[(size_t)(rowbase + tp1) * ZS + 2816 + ch]);
;       const float z3 = bf2f(z[(size_t)(rowbase + tp2) * ZS + 2816 + ch]);
; __global__ void __launch_bounds__(512) fwd_kernel(Params p) {
;     ...
;         const int tile = item - 576;
;         const int hh = tile & 3, ck = (tile >> 2) % 36, b = tile / 144;
;         rg_tile(lds, p, l, b, ck, hh, false);
.LBB0_326:
	s_andn2_b64 vcc, exec, s[0:1]
	s_cbranch_vccnz .LBB0_330
	s_add_i32 s0, s20, 0xfffffdc0
	s_lshr_b32 s1, s0, 2
	s_mul_i32 s2, s1, 0xe38f
	s_lshr_b32 s2, s2, 21
	s_mul_i32 s2, s2, 36
	s_sub_i32 s1, s1, s2
	s_mul_i32 s0, s0, 0xe38f
	s_and_b32 s2, s1, 0xffff
	s_lshr_b32 s3, s0, 23
	v_mov_b32_e32 v29, v195
	s_lshl_b32 s0, s2, 6
	s_lshl_b32 s4, s3, 8
	s_and_b32 s5, s20, 3
	s_add_i32 s1, s0, 0xffffff00
	v_ashrrev_i32_e32 v28, 6, v29
	s_add_i32 s6, s4, 0x4000
	s_lshl_b32 s7, s3, 11
	v_and_b32_e32 v6, 15, v29
	s_cmp_lt_u32 s2, 4
	s_movk_i32 s4, 0x800
	v_lshlrev_b32_e32 v0, 4, v28
	v_ashrrev_i32_e32 v35, 8, v29
	s_cselect_b32 s4, 0x100, s4
	s_cselect_b32 s9, s0, s1
	s_cselect_b32 s6, s6, s7
	v_readfirstlane_b32 s44, v195
	s_mov_b32 s47, s4
	s_mov_b32 s48, s6
	s_mov_b32 s49, s9
	s_lshl_b32 s50, s5, 7
	s_lshr_b32 s44, s44, 6
	s_lshl_b32 s45, s44, 3
	s_add_i32 s45, s45, s49
	s_add_i32 s46, s47, -1
	s_addk_i32 s50, 0x1600
	v_and_b32_e32 v185, 63, v195
	v_lshl_add_u32 v180, v185, 1, s50
	v_readlane_b32 s52, v254, 3
	v_readlane_b32 s53, v254, 4
	s_lshl_b32 s51, s5, 8
	v_lshl_add_u32 v181, v185, 2, s51
	s_nop 4
	global_load_dword v165, v181, s[52:53]
	global_load_dword v166, v181, s[52:53] offset:1024
	global_load_dword v167, v181, s[52:53] offset:2048
	global_load_dword v168, v181, s[52:53] offset:3072
	s_add_i32 s54, s45, s48
	s_mul_i32 s54, s54, 0x1a00
	v_add_u32_e32 v181, s54, v180
	s_add_i32 s55, s45, -1
	s_max_i32 s55, s55, 0
	s_add_i32 s55, s55, s48
	s_mul_i32 s55, s55, 0x1a00
	v_add_u32_e32 v184, s55, v180
	global_load_ushort v154, v184, s[88:89]
	global_load_ushort v155, v181, s[88:89]
	v_add_u32_e32 v181, 0x1a00, v181
	global_load_ushort v156, v181, s[88:89]
	v_add_u32_e32 v181, 0x1a00, v181
	global_load_ushort v157, v181, s[88:89]
	v_add_u32_e32 v181, 0x1a00, v181
	global_load_ushort v158, v181, s[88:89]
	v_add_u32_e32 v181, 0x1a00, v181
	global_load_ushort v159, v181, s[88:89]
	v_add_u32_e32 v181, 0x1a00, v181
	global_load_ushort v160, v181, s[88:89]
	v_add_u32_e32 v181, 0x1a00, v181
	global_load_ushort v161, v181, s[88:89]
	v_add_u32_e32 v181, 0x1a00, v181
	global_load_ushort v162, v181, s[88:89]
	s_add_i32 s55, s45, 8
	s_min_i32 s55, s55, s46
	s_add_i32 s55, s55, s48
	s_mul_i32 s55, s55, 0x1a00
	v_add_u32_e32 v184, s55, v180
	global_load_ushort v163, v184, s[88:89]
	s_add_i32 s55, s45, 9
	s_min_i32 s55, s55, s46
	s_add_i32 s55, s55, s48
	s_mul_i32 s55, s55, 0x1a00
	v_add_u32_e32 v184, s55, v180
	global_load_ushort v164, v184, s[88:89]
	s_mul_i32 s55, s44, 0x820
	v_lshl_add_u32 v182, v185, 2, s55
	s_mul_i32 s55, s44, 0x480
	v_lshl_add_u32 v183, v185, 1, s55
	s_lshl_b32 s0, s5, 6
	v_and_or_b32 v34, v0, 48, v6
	v_lshlrev_b32_e32 v0, 9, v35
	v_or_b32_e32 v2, s0, v34
	v_ashrrev_i32_e32 v1, 31, v0
	v_lshl_add_u64 v[0:1], v[0:1], 2, s[16:17]
	v_lshlrev_b32_e32 v192, 2, v2
	v_lshl_or_b32 v7, v35, 1, 1
	v_lshl_add_u64 v[2:3], v[0:1], 0, v[192:193]
	v_lshlrev_b32_e32 v0, 8, v7
	v_ashrrev_i32_e32 v1, 31, v0
	v_lshl_add_u64 v[0:1], v[0:1], 2, s[16:17]
	v_lshl_add_u64 v[4:5], v[0:1], 0, v[192:193]
	v_and_b32_e32 v0, 0xffffff00, v29
	v_readlane_b32 s22, v254, 1
	v_lshlrev_b32_e32 v18, 3, v28
	v_ashrrev_i32_e32 v1, 31, v0
	v_readlane_b32 s23, v254, 2
	v_add_u32_e32 v26, s9, v18
	v_and_b32_e32 v31, 63, v29
	v_lshl_add_u64 v[0:1], v[0:1], 2, s[22:23]
	v_lshl_add_u64 v[12:13], v[0:1], 0, v[192:193]
	s_add_i32 s8, s6, -1
	v_or_b32_e32 v30, s0, v31
	v_mov_b64_e32 v[0:1], s[88:89]
	v_lshlrev_b32_e32 v192, 1, v30
	s_add_i32 s7, s4, -1
	s_movk_i32 s21, 0x1000
	s_nop 0
	s_nop 0
	v_readlane_b32 s0, v254, 3
	s_nop 0
	s_nop 0
	v_lshlrev_b32_e32 v19, 2, v30
	v_readlane_b32 s1, v254, 4
	s_nop 4
	global_load_dword v10, v19, s[0:1] offset:1024
	global_load_dword v8, v19, s[0:1] offset:2048
	global_load_dword v9, v19, s[0:1] offset:3072
	global_load_dword v11, v19, s[0:1]
	global_load_dword v33, v[2:3], off
	global_load_dword v32, v[4:5], off
	global_load_dword v16, v[12:13], off
	s_nop 0
	s_nop 0
	s_nop 0
	s_nop 0
	s_movk_i32 s22, 0x104
	s_movk_i32 s9, 0x90
	v_or_b32_e32 v49, 7, v26
	v_add_u32_e32 v50, 8, v26
	v_add_u32_e32 v51, 9, v26
	v_ashrrev_i32_e32 v58, 3, v29
	s_nop 0
	s_nop 0
	s_nop 0
	s_nop 0
	s_nop 0
	s_nop 0
	s_nop 0
	s_nop 0
	s_nop 0
	s_nop 0
	s_nop 0
	v_min_i32_e32 v38, s7, v51
	s_nop 0
	s_nop 0
	s_nop 0
	s_nop 0
	v_min_i32_e32 v24, s7, v50
	v_add_u32_e32 v3, s6, v24
	s_nop 0
	v_mad_i64_i32 v[24:25], s[0:1], v3, s92, v[0:1]
	v_lshl_add_u64 v[24:25], v[24:25], 0, v[192:193]
	v_max_i32_e32 v3, 1, v49
	v_add_co_u32_e64 v24, s[0:1], s21, v24
	v_add_u32_e32 v3, s8, v3
	s_nop 0
	v_addc_co_u32_e64 v25, s[0:1], 0, v25, s[0:1]
	v_mad_u64_u32 v[26:27], s[0:1], v3, s92, v[0:1]
	v_lshl_add_u64 v[26:27], v[26:27], 0, v[192:193]
	v_add_co_u32_e64 v26, s[0:1], s21, v26
	v_add_u32_e32 v3, s6, v49
	s_nop 0
	v_addc_co_u32_e64 v27, s[0:1], 0, v27, s[0:1]
	v_mad_i64_i32 v[36:37], s[0:1], v3, s92, v[0:1]
	v_lshl_add_u64 v[36:37], v[36:37], 0, v[192:193]
	v_add_co_u32_e64 v36, s[0:1], s21, v36
	s_nop 1
	v_addc_co_u32_e64 v37, s[0:1], 0, v37, s[0:1]
	global_load_ushort v56, v[24:25], off offset:1536
	global_load_ushort v57, v[26:27], off offset:1536
	s_nop 0
	global_load_ushort v37, v[36:37], off offset:1536
	v_add_u32_e32 v12, s6, v38
	v_mad_i64_i32 v[0:1], s[0:1], v12, s92, v[0:1]
	v_lshl_add_u64 v[0:1], v[0:1], 0, v[192:193]
	v_add_co_u32_e64 v0, s[0:1], s21, v0
	v_lshlrev_b32_e32 v12, 4, v29
	s_nop 0
	v_addc_co_u32_e64 v1, s[0:1], 0, v1, s[0:1]
	v_readlane_b32 s0, v254, 5
	v_ashrrev_i32_e32 v36, 7, v29
	s_or_b32 s0, s5, s0
	v_and_b32_e32 v26, 0x70, v12
	v_and_b32_e32 v12, -4, v36
	v_add_u32_e32 v12, s0, v12
	v_ashrrev_i32_e32 v13, 31, v12
	v_readlane_b32 s6, v251, 22
; __device__ __forceinline__ bf16_t f2bf(float f) { return (bf16_t)(pack2(f, 0.f) & 0xffffu); }
; __device__ __forceinline__ float bf2f(bf16_t h) { return __uint_as_float(((unsigned)h) << 16); }
; __device__ void rg_tile(unsigned char* lds, const Params& p, int l, int b, int ck, int hh, bool outmode) {
;     ...
;     const int i = tid & 63, tq = tid >> 6;
;     const int ch = hh * 64 + i;
;     const float* wc = p.in[20] + (size_t)l * 4 * 256 + ch;
;     const float w0 = wc[0], w1 = wc[256], w2 = wc[512], w3 = wc[768];
; #pragma unroll
;     for (int ii = 0; ii < 8; ++ii) {
;       const int tt = tq * 8 + ii;
;       const int tp = t0 + tt;
;       const int tm1 = tp - 1 >= 0 ? tp - 1 : 0, tp1 = tp + 1 < L ? tp + 1 : L - 1, tp2 = tp + 2 < L ? tp + 2 : L - 1;
;       const float z0 = bf2f(z[(size_t)(rowbase + tm1) * ZS + 2816 + ch]);
;       const float z1 = bf2f(z[(size_t)(rowbase + tp) * ZS + 2816 + ch]);
;       const float z2 = bf2f(z[(size_t)(rowbase + tp1) * ZS + 2816 + ch]);
;       const float z3 = bf2f(z[(size_t)(rowbase + tp2) * ZS + 2816 + ch]);
;       float xr = w1 * z1;
;       xr += (tp - 1 >= 0 ? w0 : 0.f) * z0;
;       xr += (tp + 1 < L ? w2 : 0.f) * z2;
;       xr += (tp + 2 < L ? w3 : 0.f) * z3;
;       XR[tt * 65 + i] = xr;
;       XB[tt * 72 + i] = f2bf(xr);
;     }
;     const bf16_t* rgw = (const bf16_t*)(p.ws + OFF_RGW);
; #pragma unroll
;     for (int q = 0; q < 4; ++q) {
;       const int id = tid + 512 * q;
;       const int row = id >> 3, kc = id & 7;
;       *(uint4*)(WT + row * 72 + kc * 8) = *(const uint4*)(rgw + ((size_t)((l * 4 + (row >> 6)) * 4 + hh)) * 4096 + (row & 63) * 64 + kc * 8);
;     }
;   }
;   __syncthreads();
	v_lshlrev_b64 v[12:13], 13, v[12:13]
	v_readlane_b32 s7, v251, 23
	v_lshlrev_b32_e32 v14, 7, v58
	v_and_b32_e32 v192, 0x1f80, v14
	v_lshl_add_u64 v[12:13], s[6:7], 0, v[12:13]
	v_lshl_add_u64 v[12:13], v[12:13], 0, v[192:193]
	v_mov_b32_e32 v27, v193
	v_lshl_add_u64 v[12:13], v[12:13], 0, v[26:27]
	global_load_ushort v59, v[0:1], off offset:1536
	s_nop 0
	global_load_dwordx4 v[12:15], v[12:13], off
	v_add_u32_e32 v0, 0x200, v29
	v_ashrrev_i32_e32 v60, 3, v0
	v_lshlrev_b32_e32 v18, 7, v60
	v_ashrrev_i32_e32 v0, 7, v0
	v_and_b32_e32 v192, 0x1f80, v18
	v_add_u32_e32 v18, 0x400, v29
	v_and_b32_e32 v0, -4, v0
	v_ashrrev_i32_e32 v61, 3, v18
	v_ashrrev_i32_e32 v18, 7, v18
	v_add_u32_e32 v0, s0, v0
	v_and_b32_e32 v18, -4, v18
	v_ashrrev_i32_e32 v1, 31, v0
	v_add_u32_e32 v18, s0, v18
	v_lshlrev_b64 v[0:1], 13, v[0:1]
	v_ashrrev_i32_e32 v19, 31, v18
	v_lshl_add_u64 v[0:1], s[6:7], 0, v[0:1]
	v_lshlrev_b64 v[18:19], 13, v[18:19]
	v_lshlrev_b32_e32 v20, 7, v61
	v_lshl_add_u64 v[0:1], v[0:1], 0, v[192:193]
	v_lshl_add_u64 v[18:19], s[6:7], 0, v[18:19]
	v_and_b32_e32 v192, 0x1f80, v20
	v_lshl_add_u64 v[18:19], v[18:19], 0, v[192:193]
	v_lshl_add_u64 v[0:1], v[0:1], 0, v[26:27]
	v_lshl_add_u64 v[22:23], v[18:19], 0, v[26:27]
	global_load_dwordx4 v[18:21], v[0:1], off
	s_nop 0
	global_load_dwordx4 v[22:25], v[22:23], off
	v_add_u32_e32 v0, 0x600, v29
	v_ashrrev_i32_e32 v62, 3, v0
	v_ashrrev_i32_e32 v0, 7, v0
	v_and_b32_e32 v0, -4, v0
	v_add_u32_e32 v0, s0, v0
	v_ashrrev_i32_e32 v1, 31, v0
	v_lshlrev_b64 v[0:1], 13, v[0:1]
	v_lshlrev_b32_e32 v38, 7, v62
	v_lshl_add_u64 v[0:1], s[6:7], 0, v[0:1]
	v_and_b32_e32 v192, 0x1f80, v38
	v_lshl_add_u64 v[0:1], v[0:1], 0, v[192:193]
	v_lshl_add_u64 v[0:1], v[0:1], 0, v[26:27]
	global_load_dwordx4 v[38:41], v[0:1], off
	v_cmp_gt_i32_e32 vcc, s4, v50
	s_waitcnt vmcnt(0)
	v_lshlrev_b32_e32 v27, 16, v56
	v_lshlrev_b32_e32 v1, 16, v37
	v_cmp_lt_i32_e64 s[0:1], 0, v49
	v_lshlrev_b32_e32 v0, 16, v57
	v_mul_f32_e32 v1, v10, v1
	v_cndmask_b32_e64 v5, 0, v11, s[0:1]
	v_fmac_f32_e32 v1, v5, v0
	v_cndmask_b32_e32 v0, 0, v8, vcc
	v_cmp_gt_i32_e32 vcc, s4, v51
	v_lshlrev_b32_e32 v3, 16, v59
	v_fmac_f32_e32 v1, v0, v27
	v_cndmask_b32_e32 v0, 0, v9, vcc
	v_fmac_f32_e32 v1, v0, v3
	v_add_u32_e32 v0, 0, v26
	v_mad_u64_u32 v[2:3], s[0:1], v58, s9, v[0:1]
	ds_write_b128 v2, v[12:15] offset:25856
	v_mad_u64_u32 v[2:3], s[0:1], v60, s9, v[0:1]
	ds_write_b128 v2, v[18:21] offset:25856
	v_mad_u64_u32 v[2:3], s[0:1], v61, s9, v[0:1]
	v_mad_u64_u32 v[0:1], s[0:1], v62, s9, v[0:1]
	ds_write_b128 v2, v[22:25] offset:25856
	ds_write_b128 v0, v[38:41] offset:25856
	v_and_b32_e32 v0, 48, v29
	v_add_u32_e32 v0, 0, v0
	v_mad_u32_u24 v17, v6, s9, v0
	s_waitcnt vmcnt(0)
	v_lshlrev_b32_e32 v154, 16, v154
	v_lshlrev_b32_e32 v155, 16, v155
	v_lshlrev_b32_e32 v156, 16, v156
	v_lshlrev_b32_e32 v157, 16, v157
	v_lshlrev_b32_e32 v158, 16, v158
	v_lshlrev_b32_e32 v159, 16, v159
	v_lshlrev_b32_e32 v160, 16, v160
	v_lshlrev_b32_e32 v161, 16, v161
	v_lshlrev_b32_e32 v162, 16, v162
	v_lshlrev_b32_e32 v163, 16, v163
	v_lshlrev_b32_e32 v164, 16, v164
	s_cmp_ge_i32 s45, 1
	s_cselect_b64 s[56:57], -1, 0
	s_add_i32 s55, s45, 8
	s_cmp_lt_i32 s55, s47
	s_cselect_b64 s[58:59], -1, 0
	v_cndmask_b32_e64 v169, 0, v165, s[56:57]
	v_cndmask_b32_e64 v170, 0, v167, s[58:59]
	v_cndmask_b32_e64 v171, 0, v168, s[58:59]
	v_mul_f32_e32 v172, v166, v155
	v_fmac_f32_e32 v172, v169, v154
	v_fmac_f32_e32 v172, v167, v156
	v_fmac_f32_e32 v172, v168, v157
	v_mul_f32_e32 v173, v166, v156
	v_fmac_f32_e32 v173, v165, v155
	v_fmac_f32_e32 v173, v167, v157
	v_fmac_f32_e32 v173, v168, v158
	v_mul_f32_e32 v174, v166, v157
	v_fmac_f32_e32 v174, v165, v156
	v_fmac_f32_e32 v174, v167, v158
	v_fmac_f32_e32 v174, v168, v159
	v_mul_f32_e32 v175, v166, v158
	v_fmac_f32_e32 v175, v165, v157
	v_fmac_f32_e32 v175, v167, v159
	v_fmac_f32_e32 v175, v168, v160
	v_mul_f32_e32 v176, v166, v159
	v_fmac_f32_e32 v176, v165, v158
	v_fmac_f32_e32 v176, v167, v160
	v_fmac_f32_e32 v176, v168, v161
	v_mul_f32_e32 v177, v166, v160
	v_fmac_f32_e32 v177, v165, v159
	v_fmac_f32_e32 v177, v167, v161
	v_fmac_f32_e32 v177, v168, v162
	v_mul_f32_e32 v178, v166, v161
	v_fmac_f32_e32 v178, v165, v160
	v_fmac_f32_e32 v178, v167, v162
	v_fmac_f32_e32 v178, v171, v163
	v_mul_f32_e32 v179, v166, v162
	v_fmac_f32_e32 v179, v165, v161
	v_fmac_f32_e32 v179, v170, v163
	v_fmac_f32_e32 v179, v171, v164
	v_cvt_pk_bf16_f32 v184, v172, v172
	ds_write_b32 v182, v172
	ds_write_b16 v183, v184 offset:16640
	v_cvt_pk_bf16_f32 v184, v173, v173
	ds_write_b32 v182, v173 offset:260
	ds_write_b16 v183, v184 offset:16784
	v_cvt_pk_bf16_f32 v184, v174, v174
	ds_write_b32 v182, v174 offset:520
	ds_write_b16 v183, v184 offset:16928
	v_cvt_pk_bf16_f32 v184, v175, v175
	ds_write_b32 v182, v175 offset:780
	ds_write_b16 v183, v184 offset:17072
	v_cvt_pk_bf16_f32 v184, v176, v176
	ds_write_b32 v182, v176 offset:1040
	ds_write_b16 v183, v184 offset:17216
	v_cvt_pk_bf16_f32 v184, v177, v177
	ds_write_b32 v182, v177 offset:1300
	ds_write_b16 v183, v184 offset:17360
	v_cvt_pk_bf16_f32 v184, v178, v178
	ds_write_b32 v182, v178 offset:1560
	ds_write_b16 v183, v184 offset:17504
	v_cvt_pk_bf16_f32 v184, v179, v179
	ds_write_b32 v182, v179 offset:1820
	ds_write_b16 v183, v184 offset:17648
	s_waitcnt lgkmcnt(0)
	s_barrier
; __device__ __forceinline__ float fexp(float x) { return __expf(x); }
; __device__ __forceinline__ float sigm(float x) { return frcp(1.f + fexp(-x)); }
; __device__ __forceinline__ float logsig(float x) { return fminf(x, 0.f) - __logf(1.f + fexp(-fabsf(x))); }
; __device__ __forceinline__ float softplusf(float x) { return fmaxf(x, 0.f) + __logf(1.f + fexp(-fabsf(x))); }
; __device__ void rg_tile(unsigned char* lds, const Params& p, int l, int b, int ck, int hh, bool outmode) {
;     ...
;   {
;     const int d = w >> 2, jf = w & 3;
;     f32x4 ar[4], ai[4];
; #pragma unroll
;     for (int i = 0; i < 4; ++i) { ar[i] = (f32x4){0.f, 0.f, 0.f, 0.f}; ai[i] = (f32x4){0.f, 0.f, 0.f, 0.f}; }
; #pragma unroll
;     for (int ks = 0; ks < 2; ++ks) {
;       const bf16x8 wr = ldfrag(WT + ((d * 2 + 0) * 64 + jf * 16 + lr) * 72 + ks * 32 + lg * 8);
;       const bf16x8 wi = ldfrag(WT + ((d * 2 + 1) * 64 + jf * 16 + lr) * 72 + ks * 32 + lg * 8);
; #pragma unroll
;       for (int tf = 0; tf < 4; ++tf) {
;         const bf16x8 xf = ldfrag(XB + (tf * 16 + lr) * 72 + ks * 32 + lg * 8);
;         ar[tf] = mfma16(xf, wr, ar[tf]);
;         ai[tf] = mfma16(xf, wi, ai[tf]);
;       }
;     }
;     const int j = jf * 16 + lr;
;     const int ch = hh * 64 + j;
;     const float sp = softplusf(-lam_);
; #pragma unroll
;     for (int tf = 0; tf < 4; ++tf)
; #pragma unroll
;       for (int jj = 0; jj < 4; ++jj) {
;         const int tt = tf * 16 + lg * 4 + jj;
;         const float r = sigm(ar[tf][jj] + br);
;         const float ig = sigm(ai[tf][jj] + bi);
;         const float la = -8.0f * r * sp;
;         const float a = fexp(la);
;         const float bq = __builtin_amdgcn_sqrtf(fmaxf(1.f - a * a, 0.f)) * ig * XR[tt * 65 + j];
;         AA[(d * 64 + tt) * 64 + j] = a;
;         BQ[(d * 64 + tt) * 64 + j] = bq;
;       }
	ds_read_b128 v[18:21], v17 offset:16640
	v_lshl_or_b32 v1, v35, 7, v34
	v_mad_u64_u32 v[2:3], s[0:1], v1, s9, v[0:1]
	v_lshl_or_b32 v1, v7, 6, v34
	ds_read_b128 v[12:15], v2 offset:25856
	v_mad_u64_u32 v[0:1], s[0:1], v1, s9, v[0:1]
	ds_read_b128 v[4:7], v2 offset:25920
	ds_read_b128 v[22:25], v17 offset:16704
	ds_read_b128 v[8:11], v0 offset:25856
	ds_read_b128 v[0:3], v0 offset:25920
	s_mov_b32 s0, 0xbfb8aa3b
	v_mul_f32_e64 v26, |v16|, s0
	s_waitcnt lgkmcnt(4)
	v_mfma_f32_16x16x32_bf16 v[38:41], v[18:21], v[12:15], 0
	v_exp_f32_e32 v26, v26
	s_mov_b32 s0, 0x800000
	v_max_f32_e64 v16, -v16, -v16
	s_waitcnt lgkmcnt(1)
	v_mfma_f32_16x16x32_bf16 v[18:21], v[18:21], v[8:11], 0
	v_max_f32_e32 v16, 0, v16
	v_bfe_u32 v62, v29, 4, 2
	ds_read_b128 v[42:45], v17 offset:18944
	ds_read_b128 v[46:49], v17 offset:19008
	s_waitcnt lgkmcnt(2)
	v_mfma_f32_16x16x32_bf16 v[54:57], v[22:25], v[0:3], v[18:21]
	v_lshlrev_b32_e32 v35, 12, v35
	s_nop 1
	v_add_f32_e32 v18, 1.0, v26
	v_cmp_gt_f32_e32 vcc, s0, v18
	v_mfma_f32_16x16x32_bf16 v[38:41], v[22:25], v[4:7], v[38:41]
	s_mov_b32 s0, 0x3f317217
	v_cndmask_b32_e64 v19, 0, 32, vcc
	v_ldexp_f32 v18, v18, v19
	v_log_f32_e32 v18, v18
	v_mov_b32_e32 v20, 0x41b17218
	v_cndmask_b32_e32 v20, 0, v20, vcc
	s_nop 1
	v_add_f32_e32 v39, v33, v39
	v_mul_f32_e32 v19, 0x3f317217, v18
	v_fma_f32 v19, v18, s0, -v19
	v_fmac_f32_e32 v19, 0x3377d1cf, v18
	s_mov_b32 s0, 0x7f800000
	v_fmac_f32_e32 v19, 0x3f317217, v18
	v_cmp_lt_f32_e64 s[0:1], |v18|, s0
	ds_read_b128 v[58:61], v17 offset:21248
	ds_read_b128 v[24:27], v17 offset:21312
	v_cndmask_b32_e64 v18, v18, v19, s[0:1]
	v_add_f32_e32 v19, v33, v38
	v_mul_f32_e32 v19, 0xbfb8aa3b, v19
	v_exp_f32_e32 v19, v19
	v_sub_f32_e32 v18, v18, v20
	v_add_f32_e32 v37, v16, v18
	v_add_f32_e32 v18, v32, v54
	v_add_f32_e32 v16, 1.0, v19
	v_rcp_f32_e32 v16, v16
	v_mul_f32_e32 v18, 0xbfb8aa3b, v18
	v_exp_f32_e32 v18, v18
	v_lshl_add_u32 v54, v34, 2, 0
	v_mul_f32_e32 v16, 0xc1000000, v16
	v_mul_f32_e32 v16, v37, v16
	v_mul_f32_e32 v16, 0x3fb8aa3b, v16
	v_exp_f32_e32 v38, v16
	v_add_f32_e32 v16, 1.0, v18
	v_rcp_f32_e32 v63, v16
	s_movk_i32 s0, 0x410
	v_fma_f32 v16, -v38, v38, 1.0
	v_max_f32_e32 v16, 0, v16
	v_sqrt_f32_e32 v64, v16
	v_mad_u32_u24 v16, v62, s0, v54
	ds_read_b32 v65, v16
	ds_read_b128 v[20:23], v17 offset:23552
	ds_read_b128 v[16:19], v17 offset:23616
	v_mul_f32_e32 v39, 0xbfb8aa3b, v39
	v_mul_f32_e32 v63, v63, v64
	v_lshlrev_b32_e32 v64, 8, v62
	v_or3_b32 v64, v64, v35, v34
	v_exp_f32_e32 v39, v39
	v_lshlrev_b32_e32 v64, 2, v64
	s_waitcnt lgkmcnt(2)
	v_mul_f32_e32 v63, v65, v63
	v_add_u32_e32 v65, 0, v64
	v_readlane_b32 s0, v253, 37
	ds_write_b32 v65, v38 offset:62720
	v_mfma_f32_16x16x32_bf16 v[50:53], v[42:45], v[12:15], 0
	v_add_u32_e32 v38, s0, v64
	ds_write_b32 v38, v63
	v_add_f32_e32 v38, 1.0, v39
	v_add_f32_e32 v39, v32, v55
	v_lshl_or_b32 v55, v62, 2, 1
	v_rcp_f32_e32 v38, v38
	v_mad_u32_u24 v54, v55, s22, v54
	v_lshlrev_b32_e32 v55, 6, v55
	v_or3_b32 v34, v55, v35, v34
	v_add_f32_e32 v35, v33, v40
	v_mul_f32_e32 v35, 0xbfb8aa3b, v35
	v_exp_f32_e32 v35, v35
	v_mul_f32_e32 v38, 0xc1000000, v38
	v_mul_f32_e32 v38, v37, v38
	v_mul_f32_e32 v38, 0x3fb8aa3b, v38
	v_mul_f32_e32 v39, 0xbfb8aa3b, v39
	v_exp_f32_e32 v38, v38
	v_add_f32_e32 v35, 1.0, v35
	v_exp_f32_e32 v39, v39
	v_rcp_f32_e32 v35, v35
	v_fma_f32 v62, -v38, v38, 1.0
	v_lshlrev_b32_e32 v34, 2, v34
	v_add_f32_e32 v39, 1.0, v39
	v_max_f32_e32 v62, 0, v62
	v_add_u32_e32 v40, 0, v34
	v_mul_f32_e32 v35, 0xc1000000, v35
	v_rcp_f32_e32 v39, v39
	v_sqrt_f32_e32 v62, v62
	ds_read_b32 v63, v54
	ds_write_b32 v40, v38 offset:62720
	v_add_f32_e32 v38, v32, v56
	v_mul_f32_e32 v35, v37, v35
	v_mul_f32_e32 v38, 0xbfb8aa3b, v38
	v_mul_f32_e32 v35, 0x3fb8aa3b, v35
	v_exp_f32_e32 v38, v38
	v_exp_f32_e32 v35, v35
	v_mul_f32_e32 v39, v39, v62
	s_waitcnt lgkmcnt(1)
	v_mul_f32_e32 v39, v63, v39
	v_add_u32_e32 v34, s0, v34
	ds_write_b32 v34, v39
	v_add_f32_e32 v34, 1.0, v38
	v_fma_f32 v38, -v35, v35, 1.0
	v_max_f32_e32 v38, 0, v38
	v_rcp_f32_e32 v34, v34
	v_sqrt_f32_e32 v38, v38
	ds_read_b32 v39, v54 offset:260
	v_mfma_f32_16x16x32_bf16 v[42:45], v[42:45], v[8:11], 0
	v_mul_f32_e32 v34, v34, v38
	v_or_b32_e32 v38, 0x200, v64
	s_waitcnt lgkmcnt(0)
	v_mul_f32_e32 v34, v34, v39
	v_add_f32_e32 v39, v33, v41
	v_mul_f32_e32 v39, 0xbfb8aa3b, v39
	v_exp_f32_e32 v39, v39
	v_add_u32_e32 v40, 0, v38
	ds_write_b32 v40, v35 offset:62720
	v_add_u32_e32 v35, s0, v38
	v_add_f32_e32 v38, 1.0, v39
	v_rcp_f32_e32 v38, v38
	v_add_f32_e32 v39, v32, v57
	v_mul_f32_e32 v39, 0xbfb8aa3b, v39
	v_mfma_f32_16x16x32_bf16 v[50:53], v[46:49], v[4:7], v[50:53]
	v_exp_f32_e32 v39, v39
	v_mul_f32_e32 v38, 0xc1000000, v38
	v_mul_f32_e32 v38, v37, v38
	v_mul_f32_e32 v38, 0x3fb8aa3b, v38
	v_exp_f32_e32 v55, v38
	ds_write_b32 v35, v34
	v_add_f32_e32 v34, 1.0, v39
	v_mfma_f32_16x16x32_bf16 v[38:41], v[46:49], v[0:3], v[42:45]
	v_fma_f32 v35, -v55, v55, 1.0
	v_max_f32_e32 v35, 0, v35
	v_rcp_f32_e32 v34, v34
	v_add_f32_e32 v42, v33, v50
	v_mul_f32_e32 v42, 0xbfb8aa3b, v42
	v_exp_f32_e32 v42, v42
	v_sqrt_f32_e32 v35, v35
	ds_read_b32 v56, v54 offset:520
	v_add_f32_e32 v38, v32, v38
	v_add_f32_e32 v42, 1.0, v42
	v_rcp_f32_e32 v42, v42
	v_mul_f32_e32 v38, 0xbfb8aa3b, v38
	v_exp_f32_e32 v38, v38
	v_mul_f32_e32 v34, v34, v35
	v_mul_f32_e32 v42, 0xc1000000, v42
	v_mul_f32_e32 v42, v37, v42
	v_mul_f32_e32 v42, 0x3fb8aa3b, v42
	v_exp_f32_e32 v46, v42
	v_or_b32_e32 v35, 0x300, v64
	s_waitcnt lgkmcnt(0)
; __device__ __forceinline__ float fexp(float x) { return __expf(x); }
; __device__ __forceinline__ float sigm(float x) { return frcp(1.f + fexp(-x)); }
; __device__ void rg_tile(unsigned char* lds, const Params& p, int l, int b, int ck, int hh, bool outmode) {
;     ...
; #pragma unroll
;     for (int tf = 0; tf < 4; ++tf)
; #pragma unroll
;       for (int jj = 0; jj < 4; ++jj) {
;         const int tt = tf * 16 + lg * 4 + jj;
;         const float r = sigm(ar[tf][jj] + br);
;         const float ig = sigm(ai[tf][jj] + bi);
;         const float la = -8.0f * r * sp;
;         const float a = fexp(la);
;         const float bq = __builtin_amdgcn_sqrtf(fmaxf(1.f - a * a, 0.f)) * ig * XR[tt * 65 + j];
;         AA[(d * 64 + tt) * 64 + j] = a;
;         BQ[(d * 64 + tt) * 64 + j] = bq;
;       }
	v_mul_f32_e32 v34, v34, v56
	v_add_u32_e32 v43, 0, v35
	v_add_u32_e32 v35, s0, v35
	ds_write_b32 v35, v34
	v_fma_f32 v35, -v46, v46, 1.0
	ds_write_b32 v43, v55 offset:62720
	v_add_f32_e32 v34, 1.0, v38
	v_max_f32_e32 v35, 0, v35
	v_rcp_f32_e32 v34, v34
	v_sqrt_f32_e32 v35, v35
	ds_read_b32 v38, v54 offset:3900
	v_add_f32_e32 v39, v32, v39
	v_mul_f32_e32 v39, 0xbfb8aa3b, v39
	v_mul_f32_e32 v34, v34, v35
	v_exp_f32_e32 v39, v39
	s_waitcnt lgkmcnt(0)
	v_mul_f32_e32 v34, v34, v38
	v_add_f32_e32 v38, v33, v51
	v_mul_f32_e32 v38, 0xbfb8aa3b, v38
	v_exp_f32_e32 v38, v38
	v_or_b32_e32 v35, 0x1000, v64
	v_add_u32_e32 v47, 0, v35
	v_add_u32_e32 v35, s0, v35
	v_add_f32_e32 v38, 1.0, v38
	v_rcp_f32_e32 v38, v38
	ds_write_b32 v35, v34
	ds_write_b32 v47, v46 offset:62720
	v_add_f32_e32 v34, 1.0, v39
	v_mul_f32_e32 v38, 0xc1000000, v38
	v_mul_f32_e32 v38, v37, v38
	v_mul_f32_e32 v38, 0x3fb8aa3b, v38
	v_exp_f32_e32 v38, v38
	v_rcp_f32_e32 v34, v34
	ds_read_b32 v39, v54 offset:4160
	v_mfma_f32_16x16x32_bf16 v[42:45], v[58:61], v[12:15], 0
	v_fma_f32 v35, -v38, v38, 1.0
	v_max_f32_e32 v35, 0, v35
	v_sqrt_f32_e32 v35, v35
	v_mfma_f32_16x16x32_bf16 v[42:45], v[24:27], v[4:7], v[42:45]
	v_mul_f32_e32 v34, v34, v35
	s_waitcnt lgkmcnt(0)
	v_mul_f32_e32 v34, v34, v39
	v_add_f32_e32 v39, v33, v52
	v_mul_f32_e32 v39, 0xbfb8aa3b, v39
	v_exp_f32_e32 v39, v39
	v_or_b32_e32 v35, 0x1100, v64
	v_add_u32_e32 v50, 0, v35
	ds_write_b32 v50, v38 offset:62720
	v_add_f32_e32 v38, 1.0, v39
	v_rcp_f32_e32 v38, v38
	v_add_f32_e32 v39, v32, v40
	v_mul_f32_e32 v39, 0xbfb8aa3b, v39
	v_exp_f32_e32 v39, v39
	v_mul_f32_e32 v38, 0xc1000000, v38
	v_mul_f32_e32 v38, v37, v38
	v_mul_f32_e32 v38, 0x3fb8aa3b, v38
	v_exp_f32_e32 v38, v38
	v_add_u32_e32 v35, s0, v35
	ds_write_b32 v35, v34
	v_add_f32_e32 v34, 1.0, v39
	v_fma_f32 v35, -v38, v38, 1.0
	v_max_f32_e32 v35, 0, v35
	v_rcp_f32_e32 v34, v34
	v_sqrt_f32_e32 v35, v35
	ds_read_b32 v39, v54 offset:4420
	v_mfma_f32_16x16x32_bf16 v[46:49], v[58:61], v[8:11], 0
	v_mul_f32_e32 v34, v34, v35
	v_or_b32_e32 v35, 0x1200, v64
	s_waitcnt lgkmcnt(0)
	v_mul_f32_e32 v34, v34, v39
	v_add_f32_e32 v39, v33, v53
	v_mul_f32_e32 v39, 0xbfb8aa3b, v39
	v_exp_f32_e32 v39, v39
	v_add_u32_e32 v40, 0, v35
	ds_write_b32 v40, v38 offset:62720
	v_add_u32_e32 v35, s0, v35
	v_add_f32_e32 v38, 1.0, v39
	v_rcp_f32_e32 v38, v38
	v_add_f32_e32 v39, v32, v41
	v_mul_f32_e32 v39, 0xbfb8aa3b, v39
	v_exp_f32_e32 v39, v39
	v_mul_f32_e32 v38, 0xc1000000, v38
	v_mul_f32_e32 v38, v37, v38
	v_mul_f32_e32 v38, 0x3fb8aa3b, v38
	v_exp_f32_e32 v38, v38
	ds_write_b32 v35, v34
	v_add_f32_e32 v34, 1.0, v39
	v_rcp_f32_e32 v34, v34
	v_fma_f32 v35, -v38, v38, 1.0
	v_max_f32_e32 v35, 0, v35
	v_sqrt_f32_e32 v35, v35
	ds_read_b32 v39, v54 offset:4680
	v_mfma_f32_16x16x32_bf16 v[24:27], v[24:27], v[0:3], v[46:49]
	v_mul_f32_e32 v34, v34, v35
	v_or_b32_e32 v35, 0x1300, v64
	s_waitcnt lgkmcnt(0)
	v_mul_f32_e32 v34, v34, v39
	v_add_f32_e32 v39, v33, v42
	v_mul_f32_e32 v39, 0xbfb8aa3b, v39
	v_exp_f32_e32 v39, v39
	v_add_u32_e32 v40, 0, v35
	ds_write_b32 v40, v38 offset:62720
	v_add_f32_e32 v24, v32, v24
	v_add_f32_e32 v38, 1.0, v39
	v_rcp_f32_e32 v38, v38
	v_mul_f32_e32 v24, 0xbfb8aa3b, v24
	v_exp_f32_e32 v24, v24
	v_add_u32_e32 v35, s0, v35
	v_mul_f32_e32 v38, 0xc1000000, v38
	v_mul_f32_e32 v38, v37, v38
	v_mul_f32_e32 v38, 0x3fb8aa3b, v38
	v_exp_f32_e32 v38, v38
	ds_write_b32 v35, v34
	v_add_f32_e32 v24, 1.0, v24
	v_rcp_f32_e32 v24, v24
	v_fma_f32 v34, -v38, v38, 1.0
	v_max_f32_e32 v34, 0, v34
	v_sqrt_f32_e32 v34, v34
	ds_read_b32 v35, v54 offset:8060
	v_mfma_f32_16x16x32_bf16 v[12:15], v[20:23], v[12:15], 0
	v_add_f32_e32 v25, v32, v25
	v_mul_f32_e32 v24, v24, v34
	v_mul_f32_e32 v25, 0xbfb8aa3b, v25
	s_waitcnt lgkmcnt(0)
	v_mul_f32_e32 v24, v24, v35
	v_add_f32_e32 v35, v33, v43
	v_mul_f32_e32 v35, 0xbfb8aa3b, v35
	v_exp_f32_e32 v35, v35
	v_mfma_f32_16x16x32_bf16 v[8:11], v[20:23], v[8:11], 0
	v_add_f32_e32 v22, v33, v44
	v_mul_f32_e32 v22, 0xbfb8aa3b, v22
	v_add_f32_e32 v35, 1.0, v35
	v_rcp_f32_e32 v35, v35
	v_exp_f32_e32 v22, v22
	v_exp_f32_e32 v25, v25
	v_or_b32_e32 v34, 0x2000, v64
	v_mul_f32_e32 v35, 0xc1000000, v35
	v_mul_f32_e32 v35, v37, v35
	v_mul_f32_e32 v35, 0x3fb8aa3b, v35
	v_exp_f32_e32 v35, v35
	v_add_f32_e32 v22, 1.0, v22
	v_rcp_f32_e32 v22, v22
	v_mfma_f32_16x16x32_bf16 v[4:7], v[16:19], v[4:7], v[12:15]
	v_add_u32_e32 v39, 0, v34
	v_add_u32_e32 v34, s0, v34
	ds_write_b32 v34, v24
	v_add_f32_e32 v14, v33, v45
	v_mul_f32_e32 v14, 0xbfb8aa3b, v14
	v_add_f32_e32 v24, 1.0, v25
	v_fma_f32 v25, -v35, v35, 1.0
	v_exp_f32_e32 v14, v14
	ds_write_b32 v39, v38 offset:62720
	v_max_f32_e32 v25, 0, v25
	v_or_b32_e32 v21, 0x2100, v64
	v_mul_f32_e32 v22, 0xc1000000, v22
	v_rcp_f32_e32 v24, v24
	v_sqrt_f32_e32 v25, v25
	ds_read_b32 v34, v54 offset:8320
	v_add_u32_e32 v23, 0, v21
	v_mul_f32_e32 v22, v37, v22
	ds_write_b32 v23, v35 offset:62720
	v_add_f32_e32 v23, v32, v26
	v_mul_f32_e32 v22, 0x3fb8aa3b, v22
	v_mul_f32_e32 v23, 0xbfb8aa3b, v23
	v_exp_f32_e32 v22, v22
	v_add_f32_e32 v14, 1.0, v14
	v_exp_f32_e32 v23, v23
	v_rcp_f32_e32 v14, v14
	v_mul_f32_e32 v20, v24, v25
	v_add_f32_e32 v4, v33, v4
	s_waitcnt lgkmcnt(1)
	v_mul_f32_e32 v20, v20, v34
	v_add_u32_e32 v21, s0, v21
	v_mul_f32_e32 v4, 0xbfb8aa3b, v4
	ds_write_b32 v21, v20
	v_fma_f32 v21, -v22, v22, 1.0
	v_exp_f32_e32 v4, v4
	v_add_f32_e32 v20, 1.0, v23
	v_max_f32_e32 v21, 0, v21
	v_or_b32_e32 v13, 0x2200, v64
	v_mul_f32_e32 v14, 0xc1000000, v14
	v_rcp_f32_e32 v20, v20
	v_sqrt_f32_e32 v21, v21
	ds_read_b32 v23, v54 offset:8580
	v_add_u32_e32 v15, 0, v13
	v_mul_f32_e32 v14, v37, v14
	ds_write_b32 v15, v22 offset:62720
	v_add_f32_e32 v15, v32, v27
	v_mul_f32_e32 v14, 0x3fb8aa3b, v14
	v_mul_f32_e32 v15, 0xbfb8aa3b, v15
	v_exp_f32_e32 v14, v14
	v_add_f32_e32 v4, 1.0, v4
	v_exp_f32_e32 v15, v15
	v_rcp_f32_e32 v4, v4
	v_mul_f32_e32 v12, v20, v21
	s_waitcnt lgkmcnt(1)
; __device__ __forceinline__ float fexp(float x) { return __expf(x); }
; __device__ __forceinline__ float sigm(float x) { return frcp(1.f + fexp(-x)); }
; __device__ void rg_tile(unsigned char* lds, const Params& p, int l, int b, int ck, int hh, bool outmode) {
;     ...
; #pragma unroll
;       for (int jj = 0; jj < 4; ++jj) {
;         const int tt = tf * 16 + lg * 4 + jj;
;         const float r = sigm(ar[tf][jj] + br);
;         const float ig = sigm(ai[tf][jj] + bi);
;         const float la = -8.0f * r * sp;
;         const float a = fexp(la);
;         const float bq = __builtin_amdgcn_sqrtf(fmaxf(1.f - a * a, 0.f)) * ig * XR[tt * 65 + j];
;         AA[(d * 64 + tt) * 64 + j] = a;
;         BQ[(d * 64 + tt) * 64 + j] = bq;
;       }
;   }
;   __syncthreads();
;   {
;     float* SEG = XR;
;     const int seg = tid >> 7, d = (tid >> 6) & 1, j = tid & 63;
;     const int ch = hh * 64 + j;
;     const size_t ci = ((size_t)(b * 36 + ck) * 2 + d) * 256 + ch;
;     float H = 0.f, Ap = 1.f;
; #pragma unroll
;     for (int q = 0; q < 16; ++q) {
;       const int pos = seg * 16 + q;
;       const int tt = d == 0 ? pos : 63 - pos;
;       const float a = AA[(d * 64 + tt) * 64 + j];
;       H = a * H + BQ[(d * 64 + tt) * 64 + j];
;       Ap *= a;
;     }
	v_mul_f32_e32 v12, v12, v23
	v_add_u32_e32 v13, s0, v13
	v_mfma_f32_16x16x32_bf16 v[0:3], v[16:19], v[0:3], v[8:11]
	v_add_f32_e32 v5, v33, v5
	ds_write_b32 v13, v12
	v_fma_f32 v13, -v14, v14, 1.0
	v_mul_f32_e32 v5, 0xbfb8aa3b, v5
	v_add_f32_e32 v12, 1.0, v15
	v_max_f32_e32 v13, 0, v13
	v_mul_f32_e32 v4, 0xc1000000, v4
	v_exp_f32_e32 v5, v5
	v_rcp_f32_e32 v12, v12
	v_sqrt_f32_e32 v13, v13
	ds_read_b32 v15, v54 offset:8840
	v_mul_f32_e32 v4, v37, v4
	v_add_f32_e32 v0, v32, v0
	v_mul_f32_e32 v4, 0x3fb8aa3b, v4
	v_mul_f32_e32 v0, 0xbfb8aa3b, v0
	v_exp_f32_e32 v4, v4
	v_exp_f32_e32 v0, v0
	v_add_f32_e32 v5, 1.0, v5
	v_mul_f32_e32 v8, v12, v13
	v_or_b32_e32 v9, 0x2300, v64
	v_rcp_f32_e32 v5, v5
	s_waitcnt lgkmcnt(0)
	v_mul_f32_e32 v8, v8, v15
	v_add_u32_e32 v10, 0, v9
	v_add_u32_e32 v9, s0, v9
	ds_write_b32 v9, v8
	v_fma_f32 v8, -v4, v4, 1.0
	ds_write_b32 v10, v14 offset:62720
	v_add_f32_e32 v0, 1.0, v0
	v_max_f32_e32 v8, 0, v8
	v_rcp_f32_e32 v0, v0
	v_sqrt_f32_e32 v8, v8
	ds_read_b32 v9, v54 offset:12220
	v_mul_f32_e32 v5, 0xc1000000, v5
	v_add_f32_e32 v1, v32, v1
	v_mul_f32_e32 v5, v37, v5
	v_mul_f32_e32 v1, 0xbfb8aa3b, v1
	v_mul_f32_e32 v5, 0x3fb8aa3b, v5
	v_exp_f32_e32 v1, v1
	v_exp_f32_e32 v5, v5
	v_mul_f32_e32 v0, v0, v8
	v_or_b32_e32 v8, 0x3000, v64
	s_waitcnt lgkmcnt(0)
	v_mul_f32_e32 v0, v0, v9
	v_add_u32_e32 v9, 0, v8
	ds_write_b32 v9, v4 offset:62720
	v_add_u32_e32 v4, s0, v8
	ds_write_b32 v4, v0
	v_add_f32_e32 v0, 1.0, v1
	v_fma_f32 v1, -v5, v5, 1.0
	v_max_f32_e32 v1, 0, v1
	v_rcp_f32_e32 v0, v0
	v_sqrt_f32_e32 v1, v1
	ds_read_b32 v4, v54 offset:12480
	v_add_f32_e32 v2, v32, v2
	v_mul_f32_e32 v2, 0xbfb8aa3b, v2
	v_mul_f32_e32 v0, v0, v1
	v_exp_f32_e32 v2, v2
	s_waitcnt lgkmcnt(0)
	v_mul_f32_e32 v0, v0, v4
	v_add_f32_e32 v4, v33, v6
	v_mul_f32_e32 v4, 0xbfb8aa3b, v4
	v_exp_f32_e32 v4, v4
	v_or_b32_e32 v1, 0x3100, v64
	v_add_u32_e32 v6, 0, v1
	v_add_u32_e32 v1, s0, v1
	v_add_f32_e32 v4, 1.0, v4
	v_rcp_f32_e32 v4, v4
	ds_write_b32 v1, v0
	ds_write_b32 v6, v5 offset:62720
	v_add_f32_e32 v0, 1.0, v2
	v_mul_f32_e32 v4, 0xc1000000, v4
	v_mul_f32_e32 v4, v37, v4
	v_mul_f32_e32 v4, 0x3fb8aa3b, v4
	v_exp_f32_e32 v4, v4
	v_rcp_f32_e32 v0, v0
	ds_read_b32 v2, v54 offset:12740
	v_add_f32_e32 v3, v32, v3
	v_fma_f32 v1, -v4, v4, 1.0
	v_max_f32_e32 v1, 0, v1
	v_sqrt_f32_e32 v1, v1
	v_mul_f32_e32 v3, 0xbfb8aa3b, v3
	v_exp_f32_e32 v3, v3
	v_lshlrev_b32_e32 v15, 4, v36
	v_mul_f32_e32 v0, v0, v1
	s_waitcnt lgkmcnt(0)
	v_mul_f32_e32 v0, v0, v2
	v_add_f32_e32 v2, v33, v7
	v_mul_f32_e32 v2, 0xbfb8aa3b, v2
	v_exp_f32_e32 v2, v2
	v_or_b32_e32 v1, 0x3200, v64
	v_add_u32_e32 v5, 0, v1
	v_add_u32_e32 v1, s0, v1
	v_add_f32_e32 v2, 1.0, v2
	v_rcp_f32_e32 v2, v2
	ds_write_b32 v1, v0
	ds_write_b32 v5, v4 offset:62720
	v_add_f32_e32 v0, 1.0, v3
	v_mul_f32_e32 v2, 0xc1000000, v2
	v_mul_f32_e32 v2, v37, v2
	v_mul_f32_e32 v2, 0x3fb8aa3b, v2
	v_exp_f32_e32 v2, v2
	v_rcp_f32_e32 v0, v0
	ds_read_b32 v3, v54 offset:13000
	v_and_b32_e32 v18, 1, v28
	v_fma_f32 v1, -v2, v2, 1.0
	v_max_f32_e32 v1, 0, v1
	v_sqrt_f32_e32 v1, v1
	v_or_b32_e32 v4, 2, v15
	v_or_b32_e32 v6, 3, v15
	v_cmp_eq_u32_e32 vcc, 0, v18
	v_mul_f32_e32 v0, v0, v1
	v_or_b32_e32 v1, 0x3300, v64
	s_waitcnt lgkmcnt(0)
	v_mul_f32_e32 v0, v0, v3
	v_add_u32_e32 v3, 0, v1
	ds_write_b32 v3, v2 offset:62720
	v_add_u32_e32 v1, s0, v1
	v_or_b32_e32 v2, 1, v15
	ds_write_b32 v1, v0
	v_sub_u32_e32 v0, 63, v15
	v_sub_u32_e32 v3, 63, v2
	v_sub_u32_e32 v5, 63, v4
	v_sub_u32_e32 v7, 63, v6
	v_cndmask_b32_e32 v0, v0, v15, vcc
	v_cndmask_b32_e32 v2, v3, v2, vcc
	v_cndmask_b32_e32 v4, v5, v4, vcc
	v_cndmask_b32_e32 v6, v7, v6, vcc
	v_lshl_or_b32 v19, v18, 12, v31
	v_lshlrev_b32_e32 v0, 6, v0
	v_lshlrev_b32_e32 v2, 6, v2
	v_lshlrev_b32_e32 v4, 6, v4
	v_lshlrev_b32_e32 v6, 6, v6
	v_add_lshl_u32 v0, v0, v19, 2
	v_add_lshl_u32 v2, v2, v19, 2
	v_add_lshl_u32 v4, v4, v19, 2
	v_add_lshl_u32 v6, v6, v19, 2
	v_add_u32_e32 v1, 0, v0
	v_add_u32_e32 v0, s0, v0
	v_add_u32_e32 v3, 0, v2
	v_add_u32_e32 v2, s0, v2
	v_add_u32_e32 v5, 0, v4
	v_add_u32_e32 v7, 0, v6
	s_waitcnt lgkmcnt(0)
	s_barrier
	v_add_u32_e32 v4, s0, v4
	v_add_u32_e32 v6, s0, v6
	ds_read_b32 v1, v1 offset:62720
	ds_read_b32 v8, v0
	ds_read_b32 v3, v3 offset:62720
	ds_read_b32 v9, v2
	ds_read_b32 v0, v5 offset:62720
	ds_read_b32 v5, v4
	ds_read_b32 v2, v7 offset:62720
	ds_read_b32 v7, v6
	s_waitcnt lgkmcnt(6)
	v_fmac_f32_e32 v8, 0, v1
	v_or_b32_e32 v6, 5, v15
	s_waitcnt lgkmcnt(4)
	v_fmac_f32_e32 v9, v8, v3
	v_sub_u32_e32 v8, 63, v6
	v_cndmask_b32_e32 v6, v8, v6, vcc
	v_lshlrev_b32_e32 v6, 6, v6
	v_add_lshl_u32 v6, v6, v19, 2
	s_waitcnt lgkmcnt(2)
	v_fmac_f32_e32 v5, v9, v0
	v_add_u32_e32 v8, 0, v6
	v_add_u32_e32 v9, s0, v6
	v_or_b32_e32 v6, 6, v15
	v_sub_u32_e32 v10, 63, v6
	v_cndmask_b32_e32 v6, v10, v6, vcc
	v_lshlrev_b32_e32 v6, 6, v6
	v_add_lshl_u32 v6, v6, v19, 2
	v_mul_f32_e32 v4, v1, v3
	v_or_b32_e32 v1, 4, v15
	v_add_u32_e32 v10, 0, v6
	v_add_u32_e32 v11, s0, v6
	v_or_b32_e32 v6, 7, v15
	v_sub_u32_e32 v3, 63, v1
	v_sub_u32_e32 v12, 63, v6
	v_cndmask_b32_e32 v1, v3, v1, vcc
	v_cndmask_b32_e32 v6, v12, v6, vcc
	v_lshlrev_b32_e32 v1, 6, v1
	v_lshlrev_b32_e32 v6, 6, v6
	v_add_lshl_u32 v1, v1, v19, 2
	v_add_lshl_u32 v6, v6, v19, 2
	v_add_u32_e32 v3, 0, v1
	v_add_u32_e32 v1, s0, v1
	v_add_u32_e32 v12, 0, v6
	v_add_u32_e32 v13, s0, v6
	ds_read_b32 v6, v3 offset:62720
	ds_read_b32 v1, v1
	ds_read_b32 v8, v8 offset:62720
	ds_read_b32 v3, v9
	ds_read_b32 v10, v10 offset:62720
	ds_read_b32 v9, v11
	ds_read_b32 v12, v12 offset:62720
	ds_read_b32 v16, v13
	s_waitcnt lgkmcnt(8)
	v_fmac_f32_e32 v7, v5, v2
	v_or_b32_e32 v5, 9, v15
	s_waitcnt lgkmcnt(6)
; __device__ void rg_tile(unsigned char* lds, const Params& p, int l, int b, int ck, int hh, bool outmode) {
;     ...
;     for (int q = 0; q < 16; ++q) {
;       const int pos = seg * 16 + q;
;       const int tt = d == 0 ? pos : 63 - pos;
;       const float a = AA[(d * 64 + tt) * 64 + j];
;       H = a * H + BQ[(d * 64 + tt) * 64 + j];
;       Ap *= a;
;     }
;     SEG[((seg * 2 + d) * 64 + j) * 2 + 0] = Ap;
;     SEG[((seg * 2 + d) * 64 + j) * 2 + 1] = H;
;     __syncthreads();
;     if (!outmode) {
;       if (seg == 0) {
;         float Ht = 0.f, At = 1.f;
; #pragma unroll
;         for (int sgi = 0; sgi < 4; ++sgi) {
;           const float as = SEG[((sgi * 2 + d) * 64 + j) * 2 + 0], hs = SEG[((sgi * 2 + d) * 64 + j) * 2 + 1];
;           Ht = as * Ht + hs;
;           At *= as;
;         }
;         agg[ci * 2 + 0] = At;
;         agg[ci * 2 + 1] = Ht;
;       }
; __global__ void __launch_bounds__(512) fwd_kernel(Params p) {
;     ...
;       } else if (item < 576 + 1152) {
;         const int tile = item - 576;
;         const int hh = tile & 3, ck = (tile >> 2) % 36, b = tile / 144;
;         rg_tile(lds, p, l, b, ck, hh, false);
	v_fmac_f32_e32 v1, v7, v6
	v_sub_u32_e32 v7, 63, v5
	v_cndmask_b32_e32 v5, v7, v5, vcc
	s_waitcnt lgkmcnt(4)
	v_fmac_f32_e32 v3, v1, v8
	v_lshlrev_b32_e32 v5, 6, v5
	s_waitcnt lgkmcnt(2)
	v_fmac_f32_e32 v9, v3, v10
	v_add_lshl_u32 v5, v5, v19, 2
	s_waitcnt lgkmcnt(0)
	v_fmac_f32_e32 v16, v9, v12
	v_add_u32_e32 v7, 0, v5
	v_add_u32_e32 v9, s0, v5
	v_or_b32_e32 v5, 10, v15
	v_sub_u32_e32 v11, 63, v5
	v_cndmask_b32_e32 v5, v11, v5, vcc
	v_lshlrev_b32_e32 v5, 6, v5
	v_or_b32_e32 v1, 8, v15
	v_add_lshl_u32 v5, v5, v19, 2
	v_sub_u32_e32 v3, 63, v1
	v_add_u32_e32 v11, 0, v5
	v_add_u32_e32 v13, s0, v5
	v_or_b32_e32 v5, 11, v15
	v_cndmask_b32_e32 v1, v3, v1, vcc
	v_sub_u32_e32 v14, 63, v5
	v_lshlrev_b32_e32 v1, 6, v1
	v_cndmask_b32_e32 v5, v14, v5, vcc
	v_add_lshl_u32 v1, v1, v19, 2
	v_lshlrev_b32_e32 v5, 6, v5
	v_add_u32_e32 v3, 0, v1
	v_add_u32_e32 v1, s0, v1
	v_add_lshl_u32 v5, v5, v19, 2
	v_add_u32_e32 v17, 0, v5
	v_add_u32_e32 v20, s0, v5
	ds_read_b32 v14, v3 offset:62720
	ds_read_b32 v5, v1
	ds_read_b32 v1, v7 offset:62720
	ds_read_b32 v3, v9
	ds_read_b32 v7, v11 offset:62720
	ds_read_b32 v9, v13
	ds_read_b32 v11, v17 offset:62720
	ds_read_b32 v13, v20
	s_waitcnt lgkmcnt(6)
	v_fmac_f32_e32 v5, v16, v14
	v_mul_f32_e32 v16, v4, v0
	v_mul_f32_e32 v16, v16, v2
	s_waitcnt lgkmcnt(4)
	v_pk_fma_f32 v[2:3], v[4:5], v[0:1], v[2:3]
	v_or_b32_e32 v0, 12, v15
	v_mov_b32_e32 v17, v3
	s_waitcnt lgkmcnt(3)
	v_pk_mul_f32 v[2:3], v[16:17], v[6:7]
	s_waitcnt lgkmcnt(2)
	v_pk_fma_f32 v[4:5], v[16:17], v[6:7], v[8:9]
	v_pk_mul_f32 v[2:3], v[2:3], v[8:9]
	v_or_b32_e32 v8, 13, v15
	v_sub_u32_e32 v9, 63, v8
	v_cndmask_b32_e32 v8, v9, v8, vcc
	v_or_b32_e32 v9, 14, v15
	v_sub_u32_e32 v17, 63, v9
	v_cndmask_b32_e32 v9, v17, v9, vcc
	v_lshlrev_b32_e32 v9, 6, v9
	v_add_lshl_u32 v9, v9, v19, 2
	v_sub_u32_e32 v6, 63, v0
	v_add_u32_e32 v20, 0, v9
	v_add_u32_e32 v22, s0, v9
	v_or_b32_e32 v9, 15, v15
	v_cndmask_b32_e32 v0, v6, v0, vcc
	v_sub_u32_e32 v15, 63, v9
	v_lshlrev_b32_e32 v0, 6, v0
	v_cndmask_b32_e32 v9, v15, v9, vcc
	v_add_lshl_u32 v0, v0, v19, 2
	v_lshlrev_b32_e32 v8, 6, v8
	v_lshlrev_b32_e32 v9, 6, v9
	v_mov_b32_e32 v4, v2
	v_add_u32_e32 v6, 0, v0
	v_add_u32_e32 v0, s0, v0
	v_add_lshl_u32 v8, v8, v19, 2
	v_add_lshl_u32 v9, v9, v19, 2
	s_waitcnt lgkmcnt(1)
	v_pk_mul_f32 v[2:3], v[2:3], v[10:11]
	v_add_u32_e32 v16, 0, v8
	v_add_u32_e32 v8, s0, v8
	v_add_u32_e32 v24, 0, v9
	v_add_u32_e32 v26, s0, v9
	ds_read_b32 v15, v6 offset:62720
	ds_read_b32 v9, v0
	ds_read_b32 v17, v16 offset:62720
	ds_read_b32 v19, v8
	ds_read_b32 v21, v20 offset:62720
	ds_read_b32 v23, v22
	ds_read_b32 v25, v24 offset:62720
	ds_read_b32 v27, v26
	v_and_b32_e32 v0, 0x1fffff80, v29
	v_lshlrev_b32_e32 v6, 6, v18
	s_waitcnt lgkmcnt(8)
	v_pk_mul_f32 v[2:3], v[2:3], v[12:13]
	v_pk_fma_f32 v[4:5], v[4:5], v[10:11], v[12:13]
	v_or3_b32 v0, v6, v0, v31
	v_mov_b32_e32 v3, v5
	v_lshl_add_u32 v6, v0, 3, 0
	s_waitcnt lgkmcnt(7)
	v_pk_mul_f32 v[4:5], v[2:3], v[14:15]
	v_mov_b32_e32 v0, v1
	v_mov_b32_e32 v8, v1
	v_pk_mul_f32 v[0:1], v[4:5], v[0:1]
	s_waitcnt lgkmcnt(6)
	v_pk_fma_f32 v[2:3], v[2:3], v[14:15], v[8:9]
	v_mov_b32_e32 v4, v7
	v_mov_b32_e32 v2, v0
	v_mov_b32_e32 v16, v7
	v_pk_mul_f32 v[0:1], v[0:1], v[4:5]
	v_mov_b32_e32 v4, v11
	v_mov_b32_e32 v18, v11
	v_pk_mul_f32 v[0:1], v[0:1], v[4:5]
	s_waitcnt lgkmcnt(4)
	v_pk_fma_f32 v[2:3], v[2:3], v[16:17], v[18:19]
	v_mov_b32_e32 v20, v15
	v_mov_b32_e32 v1, v3
	s_waitcnt lgkmcnt(3)
	v_pk_mul_f32 v[2:3], v[0:1], v[20:21]
	v_mov_b32_e32 v4, v17
	v_mov_b32_e32 v22, v17
	v_pk_mul_f32 v[2:3], v[2:3], v[4:5]
	s_waitcnt lgkmcnt(2)
	v_pk_fma_f32 v[0:1], v[0:1], v[20:21], v[22:23]
	v_mov_b32_e32 v4, v21
	v_mov_b32_e32 v0, v2
	v_mov_b32_e32 v24, v21
	v_pk_mul_f32 v[2:3], v[2:3], v[4:5]
	s_waitcnt lgkmcnt(1)
	v_mov_b32_e32 v4, v25
	v_mov_b32_e32 v26, v25
	v_pk_mul_f32 v[2:3], v[2:3], v[4:5]
	s_waitcnt lgkmcnt(0)
	v_pk_fma_f32 v[0:1], v[0:1], v[24:25], v[26:27]
	v_cmp_gt_u32_e32 vcc, s91, v29
	v_mov_b32_e32 v3, v1
	ds_write_b64 v6, v[2:3]
	s_waitcnt lgkmcnt(0)
	s_barrier
	s_add_i32 s52, s20, s90
	s_cmpk_gt_i32 s52, 0x6bf
	s_cbranch_scc1 .Lrgpf3_skip
	s_addk_i32 s52, 0xfdc0
	s_and_b32 s54, s52, 3
	s_lshr_b32 s55, s52, 2
	s_mul_hi_u32 s56, s55, 0x38e38e39
	s_lshr_b32 s56, s56, 3
	s_mul_i32 s57, s56, 36
	s_sub_i32 s55, s55, s57
	s_lshl_b32 s57, s55, 6
	s_lshl_b32 s58, s56, 8
	s_add_i32 s59, s57, 0xffffff00
	s_add_i32 s58, s58, 0x4000
	s_lshl_b32 s60, s56, 11
	s_movk_i32 s61, 0x7ff
	s_cmp_lt_i32 s55, 4
	s_cselect_b32 s61, 0xff, s61
	s_cselect_b32 s57, s57, s59
	s_cselect_b32 s58, s58, s60
	s_add_i32 s57, s57, -1
	s_lshl_b32 s54, s54, 7
	s_addk_i32 s54, 0x1600
	v_add_u32_e32 v190, s57, v195
	v_max_i32_e32 v190, 0, v190
	v_min_i32_e32 v190, s61, v190
	v_add_u32_e32 v190, s58, v190
	v_mul_u32_u24_e32 v190, 0x1a00, v190
	v_add_u32_e32 v190, s54, v190
	s_movk_i32 s59, 0x44
	v_cmp_gt_u32_e64 s[60:61], s59, v195
	s_and_saveexec_b64 s[52:53], s[60:61]
	global_load_dword v191, v190, s[88:89]
	s_mov_b64 exec, s[52:53]
.Lrgpf3_skip:
	s_and_saveexec_b64 s[0:1], vcc
	s_cbranch_execz .LBB0_329
	v_lshlrev_b32_e32 v0, 3, v29
	v_add_u32_e32 v4, 0, v0
	ds_read2st64_b64 v[0:3], v4 offset1:2
	ds_read2st64_b64 v[4:7], v4 offset0:4 offset1:6
	s_mul_i32 s3, s3, 36
	s_add_i32 s3, s3, s2
	s_lshl_b32 s2, s3, 9
	s_waitcnt lgkmcnt(1)
	v_fma_f32 v1, 0, v0, v1
	v_fmac_f32_e32 v3, v1, v2
	v_lshlrev_b32_e32 v8, 8, v28
	v_mul_f32_e32 v0, v0, v2
	s_waitcnt lgkmcnt(0)
	v_fma_f32 v1, v3, v4, v5
	v_mov_b32_e32 v5, v6
	v_or3_b32 v192, v8, s2, v30
	v_readlane_b32 s2, v251, 56
	v_pk_mul_f32 v[8:9], v[0:1], v[4:5]
	v_readlane_b32 s3, v251, 57
	v_pk_mul_f32 v[8:9], v[8:9], v[6:7]
	v_pk_fma_f32 v[0:1], v[0:1], v[4:5], v[6:7]
	v_lshl_add_u64 v[2:3], v[192:193], 3, s[2:3]
	v_mov_b32_e32 v9, v1
	global_store_dwordx2 v[2:3], v[8:9], off
